# attention loops: cross-half row-max exchange with v_permlane32_swap instead of ds_bpermute (LDS round trip off the per-tile critical chain)
# speedup vs baseline: 1.0023x; 1.0023x over previous
.LBB0_1202:
	s_and_b32 s43, s43, 1
	s_mul_i32 s44, s43, 0xa800
	s_add_i32 s44, s44, 0
	v_add3_u32 v0, s44, v213, v214
	ds_read_b128 v[2:5], v0
	ds_read_b128 v[6:9], v0 offset:32
	s_waitcnt lgkmcnt(1)
	v_mfma_f32_32x32x16_bf16 v[96:111], v[2:5], v[112:115], 0
	ds_read_b128 v[2:5], v0 offset:12800
	ds_read_b128 v[10:13], v0 offset:12832
	s_waitcnt lgkmcnt(1)
	v_mfma_f32_32x32x16_bf16 v[80:95], v[2:5], v[112:115], 0
	v_mfma_f32_32x32x16_bf16 v[96:111], v[6:9], v[116:119], v[96:111]
	ds_read_b128 v[2:5], v0 offset:64
	ds_read_b128 v[6:9], v0 offset:96
	s_waitcnt lgkmcnt(2)
	v_mfma_f32_32x32x16_bf16 v[80:95], v[10:13], v[116:119], v[80:95]
	s_waitcnt lgkmcnt(1)
	v_mfma_f32_32x32x16_bf16 v[96:111], v[2:5], v[120:123], v[96:111]
	ds_read_b128 v[2:5], v0 offset:12864
	ds_read_b128 v[10:13], v0 offset:12896
	s_waitcnt lgkmcnt(1)
	v_mfma_f32_32x32x16_bf16 v[80:95], v[2:5], v[120:123], v[80:95]
	v_mfma_f32_32x32x16_bf16 v[96:111], v[6:9], v[124:127], v[96:111]
	ds_read_b128 v[2:5], v0 offset:128
	ds_read_b128 v[6:9], v0 offset:160
	s_waitcnt lgkmcnt(2)
	v_mfma_f32_32x32x16_bf16 v[80:95], v[10:13], v[124:127], v[80:95]
	s_waitcnt lgkmcnt(1)
	v_mfma_f32_32x32x16_bf16 v[96:111], v[2:5], v[128:131], v[96:111]
	ds_read_b128 v[2:5], v0 offset:12928
	ds_read_b128 v[10:13], v0 offset:12960
	s_waitcnt lgkmcnt(1)
	v_mfma_f32_32x32x16_bf16 v[80:95], v[2:5], v[128:131], v[80:95]
	v_mfma_f32_32x32x16_bf16 v[96:111], v[6:9], v[132:135], v[96:111]
	ds_read_b128 v[2:5], v0 offset:192
	ds_read_b128 v[6:9], v0 offset:224
	s_waitcnt lgkmcnt(2)
	v_mfma_f32_32x32x16_bf16 v[80:95], v[10:13], v[132:135], v[80:95]
	s_waitcnt lgkmcnt(1)
	v_mfma_f32_32x32x16_bf16 v[96:111], v[2:5], v[136:139], v[96:111]
	ds_read_b128 v[2:5], v0 offset:12992
	ds_read_b128 v[10:13], v0 offset:13024
	s_waitcnt lgkmcnt(1)
	v_mfma_f32_32x32x16_bf16 v[80:95], v[2:5], v[136:139], v[80:95]
	v_mfma_f32_32x32x16_bf16 v[96:111], v[6:9], v[140:143], v[96:111]
	ds_read_b128 v[2:5], v0 offset:256
	ds_read_b128 v[6:9], v0 offset:288
	s_waitcnt lgkmcnt(2)
	v_mfma_f32_32x32x16_bf16 v[80:95], v[10:13], v[140:143], v[80:95]
	s_waitcnt lgkmcnt(1)
	v_mfma_f32_32x32x16_bf16 v[96:111], v[2:5], v[144:147], v[96:111]
	ds_read_b128 v[2:5], v0 offset:13056
	ds_read_b128 v[10:13], v0 offset:13088
	s_waitcnt lgkmcnt(1)
	v_mfma_f32_32x32x16_bf16 v[80:95], v[2:5], v[144:147], v[80:95]
	v_mfma_f32_32x32x16_bf16 v[96:111], v[6:9], v[148:151], v[96:111]
	ds_read_b128 v[2:5], v0 offset:320
	ds_read_b128 v[6:9], v0 offset:352
	s_waitcnt lgkmcnt(2)
	v_mfma_f32_32x32x16_bf16 v[80:95], v[10:13], v[148:151], v[80:95]
	s_waitcnt lgkmcnt(1)
	v_mfma_f32_32x32x16_bf16 v[96:111], v[2:5], v[152:155], v[96:111]
	ds_read_b128 v[2:5], v0 offset:13120
	ds_read_b128 v[10:13], v0 offset:13152
	s_waitcnt lgkmcnt(1)
	v_mfma_f32_32x32x16_bf16 v[80:95], v[2:5], v[152:155], v[80:95]
	s_waitcnt lgkmcnt(0)
	v_mfma_f32_32x32x16_bf16 v[80:95], v[10:13], v[156:159], v[80:95]
	v_mfma_f32_32x32x16_bf16 v[96:111], v[6:9], v[156:159], v[96:111]
	s_nop 10
	v_max_f32_e32 v0, v80, v80
	v_max_f32_e32 v2, v96, v96
	v_max_f32_e32 v0, v2, v0
	v_max3_f32 v0, v0, v97, v81
	s_nop 0
	v_max3_f32 v0, v0, v98, v82
	s_nop 0
	v_max3_f32 v0, v0, v99, v83
	s_nop 0
	v_max3_f32 v0, v0, v100, v84
	s_nop 0
	v_max3_f32 v0, v0, v101, v85
	s_nop 0
	v_max3_f32 v0, v0, v102, v86
	s_nop 0
	v_max3_f32 v0, v0, v103, v87
	s_nop 0
	v_max3_f32 v0, v0, v104, v88
	s_nop 0
	v_max3_f32 v0, v0, v105, v89
	s_nop 0
	v_max3_f32 v0, v0, v106, v90
	s_nop 0
	v_max3_f32 v0, v0, v107, v91
	s_nop 0
	v_max3_f32 v0, v0, v108, v92
	s_nop 0
	v_max3_f32 v0, v0, v109, v93
	s_nop 0
	v_max3_f32 v0, v0, v110, v94
	s_nop 0
	v_max3_f32 v0, v0, v111, v95
	v_mov_b32_e32 v2, v0
	v_mov_b32_e32 v242, v0
	s_nop 1
	v_permlane32_swap_b32 v2, v242
	s_waitcnt lgkmcnt(0)
	v_max3_f32 v0, v234, v2, v242
	v_cmp_eq_f32_e32 vcc, v0, v234
	s_cmp_eq_u64 vcc, exec
	s_cbranch_scc1 .LBB0_1204
	v_sub_f32_e32 v2, v234, v0
	v_exp_f32_e32 v2, v2
	s_nop 0
	v_pk_mul_f32 v[78:79], v[78:79], v[2:3] op_sel_hi:[1,0]
	v_pk_mul_f32 v[76:77], v[76:77], v[2:3] op_sel_hi:[1,0]
	v_pk_mul_f32 v[74:75], v[74:75], v[2:3] op_sel_hi:[1,0]
	v_pk_mul_f32 v[72:73], v[72:73], v[2:3] op_sel_hi:[1,0]
	v_pk_mul_f32 v[70:71], v[70:71], v[2:3] op_sel_hi:[1,0]
	v_pk_mul_f32 v[68:69], v[68:69], v[2:3] op_sel_hi:[1,0]
	v_pk_mul_f32 v[66:67], v[66:67], v[2:3] op_sel_hi:[1,0]
	v_pk_mul_f32 v[64:65], v[64:65], v[2:3] op_sel_hi:[1,0]
	v_pk_mul_f32 v[62:63], v[62:63], v[2:3] op_sel_hi:[1,0]
	v_pk_mul_f32 v[60:61], v[60:61], v[2:3] op_sel_hi:[1,0]
	v_pk_mul_f32 v[58:59], v[58:59], v[2:3] op_sel_hi:[1,0]
	v_pk_mul_f32 v[56:57], v[56:57], v[2:3] op_sel_hi:[1,0]
	v_pk_mul_f32 v[54:55], v[54:55], v[2:3] op_sel_hi:[1,0]
	v_pk_mul_f32 v[52:53], v[52:53], v[2:3] op_sel_hi:[1,0]
	v_pk_mul_f32 v[50:51], v[50:51], v[2:3] op_sel_hi:[1,0]
	v_pk_mul_f32 v[48:49], v[48:49], v[2:3] op_sel_hi:[1,0]
	v_pk_mul_f32 v[46:47], v[46:47], v[2:3] op_sel_hi:[1,0]
	v_pk_mul_f32 v[44:45], v[44:45], v[2:3] op_sel_hi:[1,0]
	v_pk_mul_f32 v[42:43], v[42:43], v[2:3] op_sel_hi:[1,0]
	v_pk_mul_f32 v[40:41], v[40:41], v[2:3] op_sel_hi:[1,0]
	v_pk_mul_f32 v[38:39], v[38:39], v[2:3] op_sel_hi:[1,0]
	v_pk_mul_f32 v[36:37], v[36:37], v[2:3] op_sel_hi:[1,0]
	v_pk_mul_f32 v[34:35], v[34:35], v[2:3] op_sel_hi:[1,0]
	v_pk_mul_f32 v[32:33], v[32:33], v[2:3] op_sel_hi:[1,0]
	v_pk_mul_f32 v[30:31], v[30:31], v[2:3] op_sel_hi:[1,0]
	v_pk_mul_f32 v[28:29], v[28:29], v[2:3] op_sel_hi:[1,0]
	v_pk_mul_f32 v[26:27], v[26:27], v[2:3] op_sel_hi:[1,0]
	v_pk_mul_f32 v[24:25], v[24:25], v[2:3] op_sel_hi:[1,0]
	v_pk_mul_f32 v[22:23], v[22:23], v[2:3] op_sel_hi:[1,0]
	v_pk_mul_f32 v[20:21], v[20:21], v[2:3] op_sel_hi:[1,0]
	v_pk_mul_f32 v[18:19], v[18:19], v[2:3] op_sel_hi:[1,0]
	v_pk_mul_f32 v[16:17], v[16:17], v[2:3] op_sel_hi:[1,0]
	v_mul_f32_e32 v233, v233, v2
	s_branch .LBB0_1205

.LBB0_2348:
	s_nop 1
	v_max_f32_e32 v1, v114, v114
	s_nop 0
	v_max_f32_e32 v212, v98, v98
	v_max_f32_e32 v1, v1, v212
	v_max3_f32 v1, v1, v115, v99
	s_nop 0
	v_max3_f32 v1, v1, v116, v100
	s_nop 0
	v_max3_f32 v1, v1, v117, v101
	s_nop 0
	v_max3_f32 v1, v1, v118, v102
	s_nop 0
	v_max3_f32 v1, v1, v119, v103
	s_nop 0
	v_max3_f32 v1, v1, v120, v104
	s_nop 0
	v_max3_f32 v1, v1, v121, v105
	s_nop 0
	v_max3_f32 v1, v1, v122, v106
	s_nop 0
	v_max3_f32 v1, v1, v123, v107
	s_nop 0
	v_max3_f32 v1, v1, v124, v108
	s_nop 0
	v_max3_f32 v1, v1, v125, v109
	s_nop 0
	v_max3_f32 v1, v1, v126, v110
	s_nop 0
	v_max3_f32 v1, v1, v127, v111
	s_nop 0
	v_max3_f32 v1, v1, v128, v112
	s_nop 0
	v_max3_f32 v1, v1, v129, v113
	v_mov_b32_e32 v212, v1
	v_mov_b32_e32 v250, v1
	s_nop 1
	v_permlane32_swap_b32 v212, v250
	s_waitcnt lgkmcnt(0)
	v_max3_f32 v1, v224, v212, v250
	v_cmp_eq_f32_e32 vcc, v1, v224
	s_cmp_eq_u64 vcc, exec
	s_cbranch_scc1 .LBB0_2350
	v_sub_f32_e32 v212, v224, v1
	v_exp_f32_e32 v212, v212
	s_nop 0
	v_mul_f32_e32 v209, v209, v212
	v_pk_mul_f32 v[64:65], v[64:65], v[212:213] op_sel_hi:[1,0]
	v_pk_mul_f32 v[62:63], v[62:63], v[212:213] op_sel_hi:[1,0]
	v_pk_mul_f32 v[60:61], v[60:61], v[212:213] op_sel_hi:[1,0]
	v_pk_mul_f32 v[58:59], v[58:59], v[212:213] op_sel_hi:[1,0]
	v_pk_mul_f32 v[56:57], v[56:57], v[212:213] op_sel_hi:[1,0]
	v_pk_mul_f32 v[54:55], v[54:55], v[212:213] op_sel_hi:[1,0]
	v_pk_mul_f32 v[52:53], v[52:53], v[212:213] op_sel_hi:[1,0]
	v_pk_mul_f32 v[50:51], v[50:51], v[212:213] op_sel_hi:[1,0]
	v_pk_mul_f32 v[48:49], v[48:49], v[212:213] op_sel_hi:[1,0]
	v_pk_mul_f32 v[46:47], v[46:47], v[212:213] op_sel_hi:[1,0]
	v_pk_mul_f32 v[44:45], v[44:45], v[212:213] op_sel_hi:[1,0]
	v_pk_mul_f32 v[42:43], v[42:43], v[212:213] op_sel_hi:[1,0]
	v_pk_mul_f32 v[40:41], v[40:41], v[212:213] op_sel_hi:[1,0]
	v_pk_mul_f32 v[38:39], v[38:39], v[212:213] op_sel_hi:[1,0]
	v_pk_mul_f32 v[36:37], v[36:37], v[212:213] op_sel_hi:[1,0]
	v_pk_mul_f32 v[34:35], v[34:35], v[212:213] op_sel_hi:[1,0]
	s_branch .LBB0_2351

.LBB0_2353:
	v_max_f32_e32 v212, v66, v66
	v_max_f32_e32 v213, v82, v82
	v_max_f32_e32 v212, v213, v212
	v_max3_f32 v212, v212, v83, v67
	s_nop 0
	v_max3_f32 v212, v212, v84, v68
	s_nop 0
	v_max3_f32 v212, v212, v85, v69
	s_nop 0
	v_max3_f32 v212, v212, v86, v70
	s_nop 0
	v_max3_f32 v212, v212, v87, v71
	s_nop 0
	v_max3_f32 v212, v212, v88, v72
	s_nop 0
	v_max3_f32 v212, v212, v89, v73
	s_nop 0
	v_max3_f32 v212, v212, v90, v74
	s_nop 0
	v_max3_f32 v212, v212, v91, v75
	s_nop 0
	v_max3_f32 v212, v212, v92, v76
	s_nop 0
	v_max3_f32 v212, v212, v93, v77
	s_nop 0
	v_max3_f32 v212, v212, v94, v78
	s_nop 0
	v_max3_f32 v212, v212, v95, v79
	s_nop 0
	v_max3_f32 v212, v212, v96, v80
	s_nop 0
	v_max3_f32 v212, v212, v97, v81
	v_mov_b32_e32 v213, v212
	v_mov_b32_e32 v250, v212
	s_nop 1
	v_permlane32_swap_b32 v213, v250
	s_waitcnt lgkmcnt(0)
	v_max3_f32 v213, v211, v213, v250
	v_cmp_eq_f32_e32 vcc, v213, v211
	s_cmp_eq_u64 vcc, exec
	s_cbranch_scc1 .LBB0_2355
	v_sub_f32_e32 v211, v211, v213
	v_exp_f32_e32 v212, v211
	s_nop 0
	v_mul_f32_e32 v208, v208, v212
	v_pk_mul_f32 v[32:33], v[32:33], v[212:213] op_sel_hi:[1,0]
	v_pk_mul_f32 v[30:31], v[30:31], v[212:213] op_sel_hi:[1,0]
	v_pk_mul_f32 v[28:29], v[28:29], v[212:213] op_sel_hi:[1,0]
	v_pk_mul_f32 v[26:27], v[26:27], v[212:213] op_sel_hi:[1,0]
	v_pk_mul_f32 v[24:25], v[24:25], v[212:213] op_sel_hi:[1,0]
	v_pk_mul_f32 v[22:23], v[22:23], v[212:213] op_sel_hi:[1,0]
	v_pk_mul_f32 v[20:21], v[20:21], v[212:213] op_sel_hi:[1,0]
	v_pk_mul_f32 v[18:19], v[18:19], v[212:213] op_sel_hi:[1,0]
	v_pk_mul_f32 v[16:17], v[16:17], v[212:213] op_sel_hi:[1,0]
	v_pk_mul_f32 v[14:15], v[14:15], v[212:213] op_sel_hi:[1,0]
	v_pk_mul_f32 v[12:13], v[12:13], v[212:213] op_sel_hi:[1,0]
	v_pk_mul_f32 v[10:11], v[10:11], v[212:213] op_sel_hi:[1,0]
	v_pk_mul_f32 v[8:9], v[8:9], v[212:213] op_sel_hi:[1,0]
	v_pk_mul_f32 v[6:7], v[6:7], v[212:213] op_sel_hi:[1,0]
	v_pk_mul_f32 v[4:5], v[4:5], v[212:213] op_sel_hi:[1,0]
	v_pk_mul_f32 v[2:3], v[2:3], v[212:213] op_sel_hi:[1,0]
	s_branch .LBB0_2356
